# barrier tree rebalanced: 16 group counters (wg&15) of 16 WGs each, poll target 16*idx
# speedup vs baseline: 1.0026x; 1.0026x over previous
; __global__ void __launch_bounds__(NT) mega(P p, int lo, int hi) {
;   extern __shared__ __attribute__((aligned(16))) char smem[];
;   const int bid = blockIdx.x, nb = gridDim.x;
_Z4mega1Pii:
	s_load_dwordx2 s[4:5], s[0:1], 0xd8
	s_load_dwordx8 s[20:27], s[0:1], 0x0
	s_load_dwordx4 s[28:31], s[0:1], 0x38
	s_load_dwordx16 s[36:51], s[0:1], 0x98
	v_writelane_b32 v251, s2, 0
	s_add_u32 s2, s0, 0xe0
	s_addc_u32 s3, s1, 0
	s_waitcnt lgkmcnt(0)
	s_load_dword s98, s[0:1], 0xe0
	s_mov_b32 s99, 0
	v_readlane_b32 s100, v251, 0
	s_cmp_lg_u32 s100, 0
	s_cbranch_scc1 .Lgs_noinit
	v_and_b32_e32 v2, 0x3ff, v0
	v_cmp_gt_u32_e32 vcc, 17, v2
	s_add_u32 s100, s50, 0x3940000
	s_addc_u32 s101, s51, 0
	v_lshlrev_b32_e32 v2, 12, v2
	v_mov_b32_e32 v3, 0
	s_and_saveexec_b64 vcc, vcc
	s_cbranch_execz .Lgs_initdone
	global_atomic_swap v2, v3, s[100:101]
	s_waitcnt vmcnt(0)

; #define RUNPH(n, body)                                   \
;   if (DUP_PH == (n) && DUP_PH == 10) { phase10<true>(p, smem, bid, nb); __syncthreads(); } \
;   if (PHON(n) && lo <= (n) && (n) < hi) { for (int rep = 0; rep < ((DUP_PH == (n) && DUP_PH != 10) ? hi - 9 : 1); rep++) { body; __syncthreads(); } }         \
;   if (lo <= (n) && (n) + 1 < hi) cg::this_grid().sync();
; __global__ void __launch_bounds__(NT) mega(P p, int lo, int hi) {
;     ...
;   RUNPH(1, phase1(p, smem, bid, nb))
.LBB0_109:
	s_load_dwordx2 s[2:3], s[0:1], 0xd8
	s_waitcnt lgkmcnt(0)
	s_cmp_gt_i32 s3, 2
	s_cselect_b64 s[2:3], -1, 0
	s_and_b64 s[4:5], s[4:5], s[2:3]
	s_andn2_b64 vcc, exec, s[4:5]
	s_cbranch_vccnz .LBB0_121
	v_and_b32_e32 v1, 0x3fffffff, v0
	v_cmp_eq_u32_e32 vcc, 0, v1
	s_barrier
	s_add_i32 s99, s99, 1
	s_and_saveexec_b64 s[4:5], vcc
	s_cbranch_execz .Lgs1_done
	v_readlane_b32 s6, v251, 15
	v_readlane_b32 s7, v251, 16
	s_add_u32 s6, s6, 0x3940000
	s_addc_u32 s7, s7, 0
	buffer_wbl2 sc1
	s_waitcnt vmcnt(0)
	v_readlane_b32 s8, v251, 0
	s_and_b32 s8, s8, 15
	s_sub_i32 s9, s98, s8
	s_add_i32 s9, s9, 15
	s_lshr_b32 s9, s9, 4
	s_lshl_b32 s8, s8, 12
	s_add_i32 s8, s8, 0x1000
	v_mov_b32_e32 v1, s8
	v_mov_b32_e32 v2, 1
	global_atomic_add v2, v1, v2, s[6:7] sc0
	s_mul_i32 s8, s99, s9
	s_waitcnt vmcnt(0)
	v_readfirstlane_b32 s9, v2
	s_add_i32 s9, s9, 1
	v_mov_b32_e32 v1, 0
	v_mov_b32_e32 v2, 1
	s_cmp_lg_u32 s9, s8
	s_cbranch_scc1 .Lgs1_nolast
	global_atomic_add v1, v2, s[6:7]
.Lgs1_nolast:
	s_lshl_b32 s8, s99, 4

; #define RUNPH(n, body)                                   \
;   if (DUP_PH == (n) && DUP_PH == 10) { phase10<true>(p, smem, bid, nb); __syncthreads(); } \
;   if (PHON(n) && lo <= (n) && (n) < hi) { for (int rep = 0; rep < ((DUP_PH == (n) && DUP_PH != 10) ? hi - 9 : 1); rep++) { body; __syncthreads(); } }         \
;   if (lo <= (n) && (n) + 1 < hi) cg::this_grid().sync();
; __global__ void __launch_bounds__(NT) mega(P p, int lo, int hi) {
;     ...
;   RUNPH(2, phase2(p, smem, bid, nb))
.LBB0_321:
	s_load_dwordx16 s[4:19], s[0:1], 0x58
	s_waitcnt lgkmcnt(0)
	v_writelane_b32 v251, s4, 29
	s_nop 1
	v_writelane_b32 v251, s5, 30
	v_writelane_b32 v251, s6, 31
	v_writelane_b32 v251, s7, 32
	v_writelane_b32 v251, s8, 33
	v_writelane_b32 v251, s9, 34
	v_writelane_b32 v251, s10, 35
	v_writelane_b32 v251, s11, 36
	v_writelane_b32 v251, s12, 37
	v_writelane_b32 v251, s13, 38
	v_writelane_b32 v251, s14, 39
	v_writelane_b32 v251, s15, 40
	v_writelane_b32 v251, s16, 41
	v_writelane_b32 v251, s17, 42
	v_writelane_b32 v251, s18, 43
	v_writelane_b32 v251, s19, 44
	s_nop 0
	v_readlane_b32 s0, v251, 21
	v_readlane_b32 s1, v251, 22
	s_cmp_gt_i32 s1, 3
	s_cselect_b64 s[0:1], -1, 0
	s_and_b64 s[2:3], s[28:29], s[0:1]
	s_andn2_b64 vcc, exec, s[2:3]
	s_cbranch_vccnz .LBB0_333
	v_and_b32_e32 v1, 0x3fffffff, v0
	v_cmp_eq_u32_e32 vcc, 0, v1
	s_barrier
	s_add_i32 s99, s99, 1
	s_and_saveexec_b64 s[2:3], vcc
	s_cbranch_execz .Lgs2_done
	v_readlane_b32 s4, v251, 15
	v_readlane_b32 s5, v251, 16
	s_add_u32 s4, s4, 0x3940000
	s_addc_u32 s5, s5, 0
	buffer_wbl2 sc1
	s_waitcnt vmcnt(0)
	v_readlane_b32 s6, v251, 0
	s_and_b32 s6, s6, 15
	s_sub_i32 s7, s98, s6
	s_add_i32 s7, s7, 15
	s_lshr_b32 s7, s7, 4
	s_lshl_b32 s6, s6, 12
	s_add_i32 s6, s6, 0x1000
	v_mov_b32_e32 v1, s6
	v_mov_b32_e32 v2, 1
	global_atomic_add v2, v1, v2, s[4:5] sc0
	s_mul_i32 s6, s99, s7
	s_waitcnt vmcnt(0)
	v_readfirstlane_b32 s7, v2
	s_add_i32 s7, s7, 1
	v_mov_b32_e32 v1, 0
	v_mov_b32_e32 v2, 1
	s_cmp_lg_u32 s7, s6
	s_cbranch_scc1 .Lgs2_nolast
	global_atomic_add v1, v2, s[4:5]
.Lgs2_nolast:
	s_lshl_b32 s6, s99, 4

; #define RUNPH(n, body)                                   \
;   if (DUP_PH == (n) && DUP_PH == 10) { phase10<true>(p, smem, bid, nb); __syncthreads(); } \
;   if (PHON(n) && lo <= (n) && (n) < hi) { for (int rep = 0; rep < ((DUP_PH == (n) && DUP_PH != 10) ? hi - 9 : 1); rep++) { body; __syncthreads(); } }         \
;   if (lo <= (n) && (n) + 1 < hi) cg::this_grid().sync();
; __global__ void __launch_bounds__(NT) mega(P p, int lo, int hi) {
;     ...
;   RUNPH(3, phase3(p, smem, bid, nb))
.LBB0_528:
	v_readlane_b32 s0, v251, 21
	v_readlane_b32 s1, v251, 22
	s_cmp_gt_i32 s1, 4
	s_cselect_b64 s[0:1], -1, 0
	s_and_b64 s[2:3], s[18:19], s[0:1]
	s_andn2_b64 vcc, exec, s[2:3]
	s_cbranch_vccnz .LBB0_540
	v_and_b32_e32 v1, 0x3fffffff, v0
	v_cmp_eq_u32_e32 vcc, 0, v1
	s_barrier
	s_add_i32 s99, s99, 1
	s_and_saveexec_b64 s[2:3], vcc
	s_cbranch_execz .Lgs3_done
	v_readlane_b32 s4, v251, 15
	v_readlane_b32 s5, v251, 16
	s_add_u32 s4, s4, 0x3940000
	s_addc_u32 s5, s5, 0
	buffer_wbl2 sc1
	s_waitcnt vmcnt(0)
	v_readlane_b32 s6, v251, 0
	s_and_b32 s6, s6, 15
	s_sub_i32 s7, s98, s6
	s_add_i32 s7, s7, 15
	s_lshr_b32 s7, s7, 4
	s_lshl_b32 s6, s6, 12
	s_add_i32 s6, s6, 0x1000
	v_mov_b32_e32 v1, s6
	v_mov_b32_e32 v2, 1
	global_atomic_add v2, v1, v2, s[4:5] sc0
	s_mul_i32 s6, s99, s7
	s_waitcnt vmcnt(0)
	v_readfirstlane_b32 s7, v2
	s_add_i32 s7, s7, 1
	v_mov_b32_e32 v1, 0
	v_mov_b32_e32 v2, 1
	s_cmp_lg_u32 s7, s6
	s_cbranch_scc1 .Lgs3_nolast
	global_atomic_add v1, v2, s[4:5]

; #define RUNPH(n, body)                                   \
;   if (DUP_PH == (n) && DUP_PH == 10) { phase10<true>(p, smem, bid, nb); __syncthreads(); } \
;   if (PHON(n) && lo <= (n) && (n) < hi) { for (int rep = 0; rep < ((DUP_PH == (n) && DUP_PH != 10) ? hi - 9 : 1); rep++) { body; __syncthreads(); } }         \
;   if (lo <= (n) && (n) + 1 < hi) cg::this_grid().sync();
; __global__ void __launch_bounds__(NT) mega(P p, int lo, int hi) {
;     ...
;   RUNPH(4, phase4(p, smem, bid, nb, 8, 16))
.LBB0_718:
	v_readlane_b32 s0, v251, 21
	v_readlane_b32 s1, v251, 22
	s_cmp_gt_i32 s1, 5
	s_cselect_b64 s[0:1], -1, 0
	s_and_b64 s[2:3], s[6:7], s[0:1]
	s_andn2_b64 vcc, exec, s[2:3]
	s_cbranch_vccnz .LBB0_730
	v_and_b32_e32 v1, 0x3fffffff, v0
	v_cmp_eq_u32_e32 vcc, 0, v1
	s_barrier
	s_add_i32 s99, s99, 1
	s_and_saveexec_b64 s[2:3], vcc
	s_cbranch_execz .Lgs4_done
	v_readlane_b32 s4, v251, 15
	v_readlane_b32 s5, v251, 16
	s_add_u32 s4, s4, 0x3940000
	s_addc_u32 s5, s5, 0
	buffer_wbl2 sc1
	s_waitcnt vmcnt(0)
	v_readlane_b32 s6, v251, 0
	s_and_b32 s6, s6, 15
	s_sub_i32 s7, s98, s6
	s_add_i32 s7, s7, 15
	s_lshr_b32 s7, s7, 4
	s_lshl_b32 s6, s6, 12
	s_add_i32 s6, s6, 0x1000
	v_mov_b32_e32 v1, s6
	v_mov_b32_e32 v2, 1
	global_atomic_add v2, v1, v2, s[4:5] sc0
	s_mul_i32 s6, s99, s7
	s_waitcnt vmcnt(0)
	v_readfirstlane_b32 s7, v2
	s_add_i32 s7, s7, 1
	v_mov_b32_e32 v1, 0
	v_mov_b32_e32 v2, 1
	s_cmp_lg_u32 s7, s6
	s_cbranch_scc1 .Lgs4_nolast
	global_atomic_add v1, v2, s[4:5]

; #define RUNPH(n, body)                                   \
;   if (DUP_PH == (n) && DUP_PH == 10) { phase10<true>(p, smem, bid, nb); __syncthreads(); } \
;   if (PHON(n) && lo <= (n) && (n) < hi) { for (int rep = 0; rep < ((DUP_PH == (n) && DUP_PH != 10) ? hi - 9 : 1); rep++) { body; __syncthreads(); } }         \
;   if (lo <= (n) && (n) + 1 < hi) cg::this_grid().sync();
; __global__ void __launch_bounds__(NT) mega(P p, int lo, int hi) {
;     ...
;   RUNPH(5, phase5(p, smem, bid, nb))
.LBB0_789:
	v_readlane_b32 s0, v251, 21
	v_readlane_b32 s1, v251, 22
	s_cmp_gt_i32 s1, 6
	s_cselect_b64 s[0:1], -1, 0
	s_and_b64 s[2:3], s[2:3], s[0:1]
	s_andn2_b64 vcc, exec, s[2:3]
	s_cbranch_vccnz .LBB0_801
	v_and_b32_e32 v2, 0x3fffffff, v0
	v_cmp_eq_u32_e32 vcc, 0, v2
	s_barrier
	s_add_i32 s99, s99, 1
	s_and_saveexec_b64 s[2:3], vcc
	s_cbranch_execz .Lgs5_done
	v_readlane_b32 s4, v251, 15
	v_readlane_b32 s5, v251, 16
	s_add_u32 s4, s4, 0x3940000
	s_addc_u32 s5, s5, 0
	buffer_wbl2 sc1
	s_waitcnt vmcnt(0)
	v_readlane_b32 s6, v251, 0
	s_and_b32 s6, s6, 15
	s_sub_i32 s7, s98, s6
	s_add_i32 s7, s7, 15
	s_lshr_b32 s7, s7, 4
	s_lshl_b32 s6, s6, 12
	s_add_i32 s6, s6, 0x1000
	v_mov_b32_e32 v2, s6
	v_mov_b32_e32 v3, 1
	global_atomic_add v3, v2, v3, s[4:5] sc0
	s_mul_i32 s6, s99, s7
	s_waitcnt vmcnt(0)
	v_readfirstlane_b32 s7, v3
	s_add_i32 s7, s7, 1
	v_mov_b32_e32 v2, 0
	v_mov_b32_e32 v3, 1
	s_cmp_lg_u32 s7, s6
	s_cbranch_scc1 .Lgs5_nolast
	global_atomic_add v2, v3, s[4:5]

; #define RUNPH(n, body)                                   \
;   if (DUP_PH == (n) && DUP_PH == 10) { phase10<true>(p, smem, bid, nb); __syncthreads(); } \
;   if (PHON(n) && lo <= (n) && (n) < hi) { for (int rep = 0; rep < ((DUP_PH == (n) && DUP_PH != 10) ? hi - 9 : 1); rep++) { body; __syncthreads(); } }         \
;   if (lo <= (n) && (n) + 1 < hi) cg::this_grid().sync();
; __global__ void __launch_bounds__(NT) mega(P p, int lo, int hi) {
;     ...
;   RUNPH(6, phase6(p, smem, bid, nb))
.LBB0_811:
	v_readlane_b32 s0, v251, 21
	v_readlane_b32 s1, v251, 22
	s_cmp_gt_i32 s1, 7
	s_cselect_b64 s[2:3], -1, 0
	s_and_b64 s[0:1], s[4:5], s[2:3]
	s_andn2_b64 vcc, exec, s[0:1]
	s_cbranch_vccnz .LBB0_823
	v_and_b32_e32 v2, 0x3fffffff, v0
	v_cmp_eq_u32_e32 vcc, 0, v2
	s_barrier
	s_add_i32 s99, s99, 1
	s_and_saveexec_b64 s[0:1], vcc
	s_cbranch_execz .Lgs6_done
	v_readlane_b32 s4, v251, 15
	v_readlane_b32 s5, v251, 16
	s_add_u32 s4, s4, 0x3940000
	s_addc_u32 s5, s5, 0
	buffer_wbl2 sc1
	s_waitcnt vmcnt(0)
	v_readlane_b32 s6, v251, 0
	s_and_b32 s6, s6, 15
	s_sub_i32 s7, s98, s6
	s_add_i32 s7, s7, 15
	s_lshr_b32 s7, s7, 4
	s_lshl_b32 s6, s6, 12
	s_add_i32 s6, s6, 0x1000
	v_mov_b32_e32 v2, s6
	v_mov_b32_e32 v3, 1
	global_atomic_add v3, v2, v3, s[4:5] sc0
	s_mul_i32 s6, s99, s7
	s_waitcnt vmcnt(0)
	v_readfirstlane_b32 s7, v3
	s_add_i32 s7, s7, 1
	v_mov_b32_e32 v2, 0
	v_mov_b32_e32 v3, 1
	s_cmp_lg_u32 s7, s6
	s_cbranch_scc1 .Lgs6_nolast
	global_atomic_add v2, v3, s[4:5]

; #define RUNPH(n, body)                                   \
;   if (DUP_PH == (n) && DUP_PH == 10) { phase10<true>(p, smem, bid, nb); __syncthreads(); } \
;   if (PHON(n) && lo <= (n) && (n) < hi) { for (int rep = 0; rep < ((DUP_PH == (n) && DUP_PH != 10) ? hi - 9 : 1); rep++) { body; __syncthreads(); } }         \
;   if (lo <= (n) && (n) + 1 < hi) cg::this_grid().sync();
; __global__ void __launch_bounds__(NT) mega(P p, int lo, int hi) {
;     ...
;   RUNPH(7, phase7(p, smem, bid, nb))
.LBB0_849:
	v_readlane_b32 s2, v251, 21
	v_readlane_b32 s3, v251, 22
	s_cmp_gt_i32 s3, 8
	s_cselect_b64 s[2:3], -1, 0
	s_and_b64 s[0:1], s[0:1], s[2:3]
	s_andn2_b64 vcc, exec, s[0:1]
	s_cbranch_vccnz .LBB0_861
	v_and_b32_e32 v2, 0x3fffffff, v0
	v_cmp_eq_u32_e32 vcc, 0, v2
	s_barrier
	s_add_i32 s99, s99, 1
	s_and_saveexec_b64 s[0:1], vcc
	s_cbranch_execz .Lgs7_done
	v_readlane_b32 s4, v251, 15
	v_readlane_b32 s5, v251, 16
	s_add_u32 s4, s4, 0x3940000
	s_addc_u32 s5, s5, 0
	buffer_wbl2 sc1
	s_waitcnt vmcnt(0)
	v_readlane_b32 s6, v251, 0
	s_and_b32 s6, s6, 15
	s_sub_i32 s7, s98, s6
	s_add_i32 s7, s7, 15
	s_lshr_b32 s7, s7, 4
	s_lshl_b32 s6, s6, 12
	s_add_i32 s6, s6, 0x1000
	v_mov_b32_e32 v2, s6
	v_mov_b32_e32 v3, 1
	global_atomic_add v3, v2, v3, s[4:5] sc0
	s_mul_i32 s6, s99, s7
	s_waitcnt vmcnt(0)
	v_readfirstlane_b32 s7, v3
	s_add_i32 s7, s7, 1
	v_mov_b32_e32 v2, 0
	v_mov_b32_e32 v3, 1
	s_cmp_lg_u32 s7, s6
	s_cbranch_scc1 .Lgs7_nolast
	global_atomic_add v2, v3, s[4:5]

; #define RUNPH(n, body)                                   \
;   if (DUP_PH == (n) && DUP_PH == 10) { phase10<true>(p, smem, bid, nb); __syncthreads(); } \
;   if (PHON(n) && lo <= (n) && (n) < hi) { for (int rep = 0; rep < ((DUP_PH == (n) && DUP_PH != 10) ? hi - 9 : 1); rep++) { body; __syncthreads(); } }         \
;   if (lo <= (n) && (n) + 1 < hi) cg::this_grid().sync();
; __global__ void __launch_bounds__(NT) mega(P p, int lo, int hi) {
;     ...
;   RUNPH(8, phase8(p, bid, nb))
.LBB0_866:
	v_readlane_b32 s2, v251, 21
	v_readlane_b32 s3, v251, 22
	s_cmp_gt_i32 s3, 9
	s_cselect_b64 s[2:3], -1, 0
	s_and_b64 s[0:1], s[0:1], s[2:3]
	s_andn2_b64 vcc, exec, s[0:1]
	s_cbranch_vccnz .LBB0_878
	v_and_b32_e32 v2, 0x3fffffff, v0
	v_cmp_eq_u32_e32 vcc, 0, v2
	s_barrier
	s_add_i32 s99, s99, 1
	s_and_saveexec_b64 s[0:1], vcc
	s_cbranch_execz .Lgs8_done
	v_readlane_b32 s4, v251, 15
	v_readlane_b32 s5, v251, 16
	s_add_u32 s4, s4, 0x3940000
	s_addc_u32 s5, s5, 0
	buffer_wbl2 sc1
	s_waitcnt vmcnt(0)
	v_readlane_b32 s6, v251, 0
	s_and_b32 s6, s6, 15
	s_sub_i32 s7, s98, s6
	s_add_i32 s7, s7, 15
	s_lshr_b32 s7, s7, 4
	s_lshl_b32 s6, s6, 12
	s_add_i32 s6, s6, 0x1000
	v_mov_b32_e32 v2, s6
	v_mov_b32_e32 v3, 1
	global_atomic_add v3, v2, v3, s[4:5] sc0
	s_mul_i32 s6, s99, s7
	s_waitcnt vmcnt(0)
	v_readfirstlane_b32 s7, v3
	s_add_i32 s7, s7, 1
	v_mov_b32_e32 v2, 0
	v_mov_b32_e32 v3, 1
	s_cmp_lg_u32 s7, s6
	s_cbranch_scc1 .Lgs8_nolast
	global_atomic_add v2, v3, s[4:5]

; #define RUNPH(n, body)                                   \
;   if (DUP_PH == (n) && DUP_PH == 10) { phase10<true>(p, smem, bid, nb); __syncthreads(); } \
;   if (PHON(n) && lo <= (n) && (n) < hi) { for (int rep = 0; rep < ((DUP_PH == (n) && DUP_PH != 10) ? hi - 9 : 1); rep++) { body; __syncthreads(); } }         \
;   if (lo <= (n) && (n) + 1 < hi) cg::this_grid().sync();
; __global__ void __launch_bounds__(NT) mega(P p, int lo, int hi) {
;     ...
;   RUNPH(9, phase9(p, smem, bid, nb))
.LBB0_900:
	v_readlane_b32 s0, v251, 21
	v_readlane_b32 s1, v251, 22
	s_cmp_gt_i32 s1, 10
	s_cselect_b64 s[0:1], -1, 0
	s_and_b64 s[2:3], s[4:5], s[0:1]
	s_andn2_b64 vcc, exec, s[2:3]
	s_cbranch_vccnz .LBB0_912
	v_and_b32_e32 v2, 0x3fffffff, v0
	v_cmp_eq_u32_e32 vcc, 0, v2
	s_barrier
	s_add_i32 s99, s99, 1
	s_and_saveexec_b64 s[2:3], vcc
	s_cbranch_execz .Lgs9_done
	v_readlane_b32 s4, v251, 15
	v_readlane_b32 s5, v251, 16
	s_add_u32 s4, s4, 0x3940000
	s_addc_u32 s5, s5, 0
	buffer_wbl2 sc1
	s_waitcnt vmcnt(0)
	v_readlane_b32 s6, v251, 0
	s_and_b32 s6, s6, 15
	s_sub_i32 s7, s98, s6
	s_add_i32 s7, s7, 15
	s_lshr_b32 s7, s7, 4
	s_lshl_b32 s6, s6, 12
	s_add_i32 s6, s6, 0x1000
	v_mov_b32_e32 v2, s6
	v_mov_b32_e32 v3, 1
	global_atomic_add v3, v2, v3, s[4:5] sc0
	s_mul_i32 s6, s99, s7
	s_waitcnt vmcnt(0)
	v_readfirstlane_b32 s7, v3
	s_add_i32 s7, s7, 1
	v_mov_b32_e32 v2, 0
	v_mov_b32_e32 v3, 1
	s_cmp_lg_u32 s7, s6
	s_cbranch_scc1 .Lgs9_nolast
	global_atomic_add v2, v3, s[4:5]
